# P8 epilogue: skip row-scale table rebuild when the unit's row panel is unchanged (on top of preheader-drain removal)
# baseline (speedup 1.0000x reference)
; #define PH(n) if (ONLY < 0 || ONLY == (n))
; #define WSB(off) ((bf16*)((unsigned char*)KARG(20) + (off)))
; #define WSF(off) ((float*)((unsigned char*)KARG(20) + (off)))
; template <class Epi, class Sched>
; __device__ __forceinline__ void gemm_phase(PG8_LAS unsigned char* lds, PG8_LAS unsigned char* xl, const Gemm g, const Sched& S, const Epi& E) {
;     ...
;     Unit cur, nxt; int ui = 0;
;     if (!S.next(0, cur)) return;
; __global__ void __launch_bounds__(NWAVES * 64, 2) mk_fwd(Args args) {
;     ...
;     PH(8) { PHASE_VARS
;         pg8::Gemm g{WSB(WS_XN), WSB(WS_WGU), DM, DM, DM}; pg8::Sched2D S; S.init(T, 2 * DFF, G, bx, DM, DM);
;         pg8::EpiSwiGLU E{WSB(WS_HMID), DFF, WSF(WS_SS2)};
;         pg8::gemm_phase(lds, xl, g, S, E);
.LBB0_814:
	s_or_b64 exec, exec, s[2:3]
	s_mov_b32 s99, -1
	v_mov_b32_e32 v0, v220
	s_mov_b32 s36, s39
	v_mov_b32_e32 v10, v220
	s_waitcnt lgkmcnt(0)
	s_load_dwordx2 s[2:3], s[0:1], 0xa0
	s_waitcnt lgkmcnt(0)
	s_load_dwordx2 s[8:9], s[0:1], 0xa0
	s_waitcnt lgkmcnt(0)
	s_load_dwordx2 s[12:13], s[0:1], 0xa0
	s_waitcnt lgkmcnt(0)
	s_load_dwordx2 s[6:7], s[0:1], 0xa0
	s_waitcnt lgkmcnt(0)
	s_cmpk_gt_i32 s36, 0xaff
	v_readfirstlane_b32 s18, v10
	s_cbranch_scc0 .LBB0_817
	s_and_saveexec_b64 s[2:3], s[48:49]
	s_xor_b64 s[48:49], exec, s[2:3]
	s_cbranch_execnz .LBB0_834

; #define PG8_LAS __attribute__((address_space(3)))
; __device__ __forceinline__ const PG8_LAS float* rs_table(const float* SS, int r0, PG8_LAS unsigned char* xl) {
;     PG8_LAS float* S = (PG8_LAS float*)(xl + 8192 + 256); const int tid = threadIdx.x;
;     if (tid < 256) { const f32x4 p = *(const f32x4*)(SS + (size_t)(r0 + tid) * 4); S[tid] = 1.0f / sqrtf(((p[0] + p[1]) + (p[2] + p[3])) * (1.f / DM) + EPS); }
;     asm volatile("s_waitcnt vmcnt(0) lgkmcnt(0)" ::: "memory"); __builtin_amdgcn_s_barrier(); asm volatile("" ::: "memory");
;     return S;
.LBB0_828:
	s_cmp_eq_u32 s60, s99
	s_cbranch_scc1 .Lrs8_skip
	s_mov_b32 s99, s60
	s_and_saveexec_b64 s[30:31], s[4:5]
	s_cbranch_execz .LBB0_830
	v_add_u32_e32 v170, s60, v220
	v_ashrrev_i32_e32 v171, 31, v170
	v_lshl_add_u64 v[170:171], v[170:171], 4, s[14:15]
	flat_load_dwordx4 v[170:173], v[170:171]
	s_waitcnt vmcnt(0) lgkmcnt(0)
	v_mov_b32_e32 v174, v171
	v_mov_b32_e32 v175, v172
	v_mov_b32_e32 v171, v173
	v_pk_add_f32 v[170:171], v[174:175], v[170:171]
	s_nop 0
	v_add_f32_e32 v169, v170, v171
	v_fmamk_f32 v169, v169, 0x3a800000, v167
	v_mul_f32_e32 v170, 0x4f800000, v169
	v_cmp_gt_f32_e32 vcc, s63, v169
	s_nop 1
	v_cndmask_b32_e32 v169, v169, v170, vcc
	v_sqrt_f32_e32 v170, v169
	s_nop 0
	v_add_u32_e32 v171, -1, v170
	v_add_u32_e32 v172, 1, v170
	v_fma_f32 v173, -v171, v170, v169
	v_fma_f32 v174, -v172, v170, v169
	v_cmp_ge_f32_e64 s[2:3], 0, v173
	s_nop 1
	v_cndmask_b32_e64 v170, v170, v171, s[2:3]
	v_cmp_lt_f32_e64 s[2:3], 0, v174
	s_nop 1
	v_cndmask_b32_e64 v170, v170, v172, s[2:3]
	v_mul_f32_e32 v171, 0x37800000, v170
	v_cndmask_b32_e32 v170, v170, v171, vcc
	v_cmp_class_f32_e32 vcc, v169, v168
	s_nop 1
	v_cndmask_b32_e32 v169, v170, v169, vcc
	v_div_scale_f32 v170, s[2:3], v169, v169, 1.0
	v_rcp_f32_e32 v171, v170
	v_div_scale_f32 v172, vcc, 1.0, v169, 1.0
	v_fma_f32 v173, -v170, v171, 1.0
	v_fmac_f32_e32 v171, v173, v171
	v_mul_f32_e32 v173, v172, v171
	v_fma_f32 v174, -v170, v173, v172
	v_fmac_f32_e32 v173, v174, v171
	v_fma_f32 v170, -v170, v173, v172
	v_div_fmas_f32 v170, v170, v171, v173
	v_div_fixup_f32 v169, v170, v169, 1.0
	ds_write_b32 v154, v169

; __device__ __forceinline__ u32x4 pack8(f32x4 v0, f32x4 v1) { u32x4 w; w.x = cvt_pk_bf16(v0[0], v0[1]); w.y = cvt_pk_bf16(v0[2], v0[3]); w.z = cvt_pk_bf16(v1[0], v1[1]); w.w = cvt_pk_bf16(v1[2], v1[3]); return w; }
;     __device__ __forceinline__ void operator()(Acc& acc, const Unit& u, int wr, int wc, int fr, int fq, PG8_LAS unsigned char* xl) const {
;     ...
;             for (int m = 0; m < 4; ++m) { const int rl = ai * HALF + wr * 64 + m * 16 + fr; const int row = u.r0 + rl; const float s = S[rl], cs = -LOG2E * s, s2 = s * s;
;                 f32x4 o[2];
; #pragma unroll
;                 for (int n = 0; n < 2; ++n) { const f32x4 g = acc[ai][0][m][n], gu = acc[ai][0][m][n] * acc[ai][1][m][n]; f32x4 r;
; #pragma unroll
;                     for (int e = 0; e < 4; ++e) r[e] = gu[e] * (s2 * __builtin_amdgcn_rcpf(1.f + __builtin_amdgcn_exp2f(cs * g[e])));
;                     o[n] = r; }
;                 *(u32x4*)(H + (size_t)row * ldc + (u.c0 >> 1) + wc * 32 + 8 * fq) = pack8(o[0], o[1]); }
.Lrs8_skip:
	ds_read_b32 v169, v148
	v_mov_b32_e32 v170, v124
	v_mov_b32_e32 v172, v120
	s_ashr_i32 s2, s33, 1
	s_ashr_i32 s3, s2, 31
	s_waitcnt lgkmcnt(0)
	v_mul_f32_e32 v174, 0xbfb8aa3b, v169
	v_mul_f32_e32 v124, v124, v174
	v_exp_f32_e32 v124, v124
	v_mul_f32_e32 v120, v125, v174
	v_exp_f32_e32 v120, v120
	v_mul_f32_e32 v171, v169, v169
	v_add_f32_e32 v124, 1.0, v124
	v_rcp_f32_e32 v173, v124
	v_add_f32_e32 v120, 1.0, v120
	s_lshl_b64 s[2:3], s[2:3], 1
	s_andn2_b64 vcc, exec, s[6:7]
	v_pk_mul_f32 v[172:173], v[170:171], v[172:173]
	v_mov_b32_e32 v170, v125
	v_mul_f32_e32 v124, v172, v173
	v_rcp_f32_e32 v173, v120
	v_mul_f32_e32 v120, v126, v174
	v_exp_f32_e32 v125, v120
	v_mov_b32_e32 v172, v121
	v_pk_mul_f32 v[120:121], v[170:171], v[172:173]
	v_mov_b32_e32 v170, v126
	v_mul_f32_e32 v169, v120, v121
	v_add_f32_e32 v120, 1.0, v125
	v_rcp_f32_e32 v121, v120
	v_mul_f32_e32 v120, v127, v174
	v_exp_f32_e32 v125, v120
	v_mov_b32_e32 v120, v122
	v_pk_mul_f32 v[120:121], v[170:171], v[120:121]
	v_mov_b32_e32 v170, v127
	v_mul_f32_e32 v122, v120, v121
	v_add_f32_e32 v120, 1.0, v125
	v_rcp_f32_e32 v121, v120
	v_mul_f32_e32 v120, v116, v174
	v_exp_f32_e32 v125, v120
	v_mov_b32_e32 v120, v123
	v_pk_mul_f32 v[120:121], v[170:171], v[120:121]
	v_mov_b32_e32 v170, v116
	v_mul_f32_e32 v123, v120, v121
	v_add_f32_e32 v120, 1.0, v125
	v_mul_f32_e32 v116, v117, v174
	v_rcp_f32_e32 v121, v120
	v_exp_f32_e32 v116, v116
	v_mov_b32_e32 v120, v112
	v_pk_mul_f32 v[120:121], v[170:171], v[120:121]
	v_add_f32_e32 v112, 1.0, v116
	v_mul_f32_e32 v125, v120, v121
	v_rcp_f32_e32 v121, v112
	v_mul_f32_e32 v112, v118, v174
	v_exp_f32_e32 v116, v112
	v_mov_b32_e32 v170, v117
	v_mov_b32_e32 v120, v113
	v_pk_mul_f32 v[112:113], v[170:171], v[120:121]
	v_mov_b32_e32 v170, v118
	v_mul_f32_e32 v120, v112, v113
	v_add_f32_e32 v112, 1.0, v116
	v_rcp_f32_e32 v113, v112
	v_mul_f32_e32 v112, v119, v174
	v_exp_f32_e32 v116, v112
	v_mov_b32_e32 v112, v114
	v_pk_mul_f32 v[112:113], v[170:171], v[112:113]
	v_mov_b32_e32 v170, v119
	v_add_f32_e32 v114, 1.0, v116
	v_rcp_f32_e32 v117, v114
	v_mov_b32_e32 v116, v115
	v_mul_f32_e32 v118, v112, v113
	v_add_u32_e32 v119, s60, v146
	v_pk_mul_f32 v[112:113], v[170:171], v[116:117]
	v_cvt_pk_bf16_f32 v114, v124, v169
	v_cvt_pk_bf16_f32 v115, v122, v123
	v_cvt_pk_bf16_f32 v116, v125, v120
	s_nop 0
	v_mul_f32_e32 v112, v112, v113
	v_cvt_pk_bf16_f32 v117, v118, v112
	v_mov_b64_e32 v[112:113], s[12:13]
	v_mad_i64_i32 v[118:119], s[30:31], v119, s64, v[112:113]
	v_lshl_add_u64 v[118:119], v[118:119], 0, s[2:3]
	v_lshl_add_u64 v[118:119], v[118:119], 0, s[8:9]
	v_lshl_add_u64 v[118:119], v[118:119], 0, v[136:137]
	flat_store_dwordx4 v[118:119], v[114:117]
	ds_read_b32 v114, v150
	s_waitcnt lgkmcnt(0)
	v_mul_f32_e32 v118, 0xbfb8aa3b, v114
	v_mul_f32_e32 v115, v108, v118
	v_exp_f32_e32 v116, v115
	v_mul_f32_e32 v115, v114, v114
	v_add_f32_e32 v114, 1.0, v116
	v_rcp_f32_e32 v117, v114
	v_mov_b32_e32 v114, v108
	v_mul_f32_e32 v108, v109, v118
	v_exp_f32_e32 v108, v108
	v_mov_b32_e32 v116, v104
	v_pk_mul_f32 v[116:117], v[114:115], v[116:117]
	v_mov_b32_e32 v114, v109
	v_add_f32_e32 v104, 1.0, v108
	v_mul_f32_e32 v119, v116, v117
	v_rcp_f32_e32 v117, v104
	v_mul_f32_e32 v104, v110, v118
	v_exp_f32_e32 v108, v104
	v_mov_b32_e32 v116, v105
	v_pk_mul_f32 v[104:105], v[114:115], v[116:117]
	v_mov_b32_e32 v114, v110
	v_mul_f32_e32 v109, v104, v105
	v_add_f32_e32 v104, 1.0, v108
	v_rcp_f32_e32 v105, v104
	v_mul_f32_e32 v104, v111, v118
	v_exp_f32_e32 v108, v104
	v_mov_b32_e32 v104, v106
	v_pk_mul_f32 v[104:105], v[114:115], v[104:105]
	v_mov_b32_e32 v114, v111
	v_mul_f32_e32 v106, v104, v105
	v_add_f32_e32 v104, 1.0, v108
	v_rcp_f32_e32 v105, v104
	v_mul_f32_e32 v104, v100, v118
	v_exp_f32_e32 v108, v104
	v_mov_b32_e32 v104, v107
	v_pk_mul_f32 v[104:105], v[114:115], v[104:105]
	v_mov_b32_e32 v114, v100
	v_mul_f32_e32 v107, v104, v105
	v_add_f32_e32 v104, 1.0, v108
	v_mul_f32_e32 v100, v101, v118
	v_rcp_f32_e32 v105, v104
	v_exp_f32_e32 v100, v100
	v_mov_b32_e32 v104, v96
	v_pk_mul_f32 v[104:105], v[114:115], v[104:105]
	v_add_f32_e32 v96, 1.0, v100
	v_mul_f32_e32 v108, v104, v105
	v_rcp_f32_e32 v105, v96
	v_mul_f32_e32 v96, v102, v118
	v_exp_f32_e32 v100, v96
	v_mov_b32_e32 v114, v101
	v_mov_b32_e32 v104, v97
	v_pk_mul_f32 v[96:97], v[114:115], v[104:105]
	v_mov_b32_e32 v114, v102
	v_mul_f32_e32 v104, v96, v97
	v_add_f32_e32 v96, 1.0, v100
	v_rcp_f32_e32 v97, v96
	v_mul_f32_e32 v96, v103, v118
	v_exp_f32_e32 v100, v96
	v_mov_b32_e32 v96, v98
	v_pk_mul_f32 v[96:97], v[114:115], v[96:97]
	v_mov_b32_e32 v114, v103
	v_add_f32_e32 v98, 1.0, v100
	v_rcp_f32_e32 v101, v98
	v_mov_b32_e32 v100, v99
	v_mul_f32_e32 v102, v96, v97
	v_pk_mul_f32 v[96:97], v[114:115], v[100:101]
	v_add_u32_e32 v100, s60, v149
	v_mad_i64_i32 v[100:101], s[30:31], v100, s64, v[112:113]
	v_lshl_add_u64 v[100:101], v[100:101], 0, s[2:3]
	v_lshl_add_u64 v[100:101], v[100:101], 0, s[8:9]
	v_mul_f32_e32 v99, v96, v97
	v_lshl_add_u64 v[100:101], v[100:101], 0, v[136:137]
	v_cvt_pk_bf16_f32 v96, v119, v109
	v_cvt_pk_bf16_f32 v97, v106, v107
	v_cvt_pk_bf16_f32 v98, v108, v104
	v_cvt_pk_bf16_f32 v99, v102, v99
	flat_store_dwordx4 v[100:101], v[96:99]
	ds_read_b32 v96, v152
	s_waitcnt lgkmcnt(0)
; __device__ __forceinline__ u32x4 pack8(f32x4 v0, f32x4 v1) { u32x4 w; w.x = cvt_pk_bf16(v0[0], v0[1]); w.y = cvt_pk_bf16(v0[2], v0[3]); w.z = cvt_pk_bf16(v1[0], v1[1]); w.w = cvt_pk_bf16(v1[2], v1[3]); return w; }
;     __device__ __forceinline__ void operator()(Acc& acc, const Unit& u, int wr, int wc, int fr, int fq, PG8_LAS unsigned char* xl) const {
;     ...
;             for (int m = 0; m < 4; ++m) { const int rl = ai * HALF + wr * 64 + m * 16 + fr; const int row = u.r0 + rl; const float s = S[rl], cs = -LOG2E * s, s2 = s * s;
;                 f32x4 o[2];
; #pragma unroll
;                 for (int n = 0; n < 2; ++n) { const f32x4 g = acc[ai][0][m][n], gu = acc[ai][0][m][n] * acc[ai][1][m][n]; f32x4 r;
; #pragma unroll
;                     for (int e = 0; e < 4; ++e) r[e] = gu[e] * (s2 * __builtin_amdgcn_rcpf(1.f + __builtin_amdgcn_exp2f(cs * g[e])));
;                     o[n] = r; }
;                 *(u32x4*)(H + (size_t)row * ldc + (u.c0 >> 1) + wc * 32 + 8 * fq) = pack8(o[0], o[1]); }
	v_mul_f32_e32 v100, 0xbfb8aa3b, v96
	v_mul_f32_e32 v97, v92, v100
	v_exp_f32_e32 v98, v97
	v_mul_f32_e32 v97, v96, v96
	v_add_f32_e32 v96, 1.0, v98
	v_rcp_f32_e32 v99, v96
	v_mov_b32_e32 v96, v92
	v_mul_f32_e32 v92, v93, v100
	v_exp_f32_e32 v92, v92
	v_mov_b32_e32 v98, v88
	v_pk_mul_f32 v[98:99], v[96:97], v[98:99]
	v_mov_b32_e32 v96, v93
	v_add_f32_e32 v88, 1.0, v92
	v_mul_f32_e32 v101, v98, v99
	v_rcp_f32_e32 v99, v88
	v_mul_f32_e32 v88, v94, v100
	v_exp_f32_e32 v92, v88
	v_mov_b32_e32 v98, v89
	v_pk_mul_f32 v[88:89], v[96:97], v[98:99]
	v_mov_b32_e32 v96, v94
	v_mul_f32_e32 v93, v88, v89
	v_add_f32_e32 v88, 1.0, v92
	v_rcp_f32_e32 v89, v88
	v_mul_f32_e32 v88, v95, v100
	v_exp_f32_e32 v92, v88
	v_mov_b32_e32 v88, v90
	v_pk_mul_f32 v[88:89], v[96:97], v[88:89]
	v_mov_b32_e32 v96, v95
	v_mul_f32_e32 v90, v88, v89
	v_add_f32_e32 v88, 1.0, v92
	v_rcp_f32_e32 v89, v88
	v_mul_f32_e32 v88, v84, v100
	v_exp_f32_e32 v92, v88
	v_mov_b32_e32 v88, v91
	v_pk_mul_f32 v[88:89], v[96:97], v[88:89]
	v_mov_b32_e32 v96, v84
	v_mul_f32_e32 v91, v88, v89
	v_add_f32_e32 v88, 1.0, v92
	v_mul_f32_e32 v84, v85, v100
	v_rcp_f32_e32 v89, v88
	v_exp_f32_e32 v84, v84
	v_mov_b32_e32 v88, v80
	v_pk_mul_f32 v[88:89], v[96:97], v[88:89]
	v_add_f32_e32 v80, 1.0, v84
	v_mul_f32_e32 v92, v88, v89
	v_rcp_f32_e32 v89, v80
	v_mul_f32_e32 v80, v86, v100
	v_exp_f32_e32 v84, v80
	v_mov_b32_e32 v96, v85
	v_mov_b32_e32 v88, v81
	v_pk_mul_f32 v[80:81], v[96:97], v[88:89]
	v_mov_b32_e32 v96, v86
	v_mul_f32_e32 v88, v80, v81
	v_add_f32_e32 v80, 1.0, v84
	v_rcp_f32_e32 v81, v80
	v_mul_f32_e32 v80, v87, v100
	v_exp_f32_e32 v84, v80
	v_mov_b32_e32 v80, v82
	v_pk_mul_f32 v[80:81], v[96:97], v[80:81]
	v_mov_b32_e32 v96, v87
	v_add_f32_e32 v82, 1.0, v84
	v_rcp_f32_e32 v85, v82
	v_mov_b32_e32 v84, v83
	v_mul_f32_e32 v86, v80, v81
	v_pk_mul_f32 v[80:81], v[96:97], v[84:85]
	v_add_u32_e32 v84, s60, v151
	v_mad_i64_i32 v[84:85], s[30:31], v84, s64, v[112:113]
	v_lshl_add_u64 v[84:85], v[84:85], 0, s[2:3]
	v_lshl_add_u64 v[84:85], v[84:85], 0, s[8:9]
	v_mul_f32_e32 v83, v80, v81
	v_lshl_add_u64 v[84:85], v[84:85], 0, v[136:137]
	v_cvt_pk_bf16_f32 v80, v101, v93
	v_cvt_pk_bf16_f32 v81, v90, v91
	v_cvt_pk_bf16_f32 v82, v92, v88
	v_cvt_pk_bf16_f32 v83, v86, v83
	flat_store_dwordx4 v[84:85], v[80:83]
	ds_read_b32 v80, v155
	s_waitcnt lgkmcnt(0)
	v_mul_f32_e32 v84, 0xbfb8aa3b, v80
	v_mul_f32_e32 v81, v76, v84
	v_exp_f32_e32 v82, v81
	v_mul_f32_e32 v81, v80, v80
	v_add_f32_e32 v80, 1.0, v82
	v_rcp_f32_e32 v83, v80
	v_mov_b32_e32 v80, v76
	v_mul_f32_e32 v76, v77, v84
	v_exp_f32_e32 v76, v76
	v_mov_b32_e32 v82, v72
	v_pk_mul_f32 v[82:83], v[80:81], v[82:83]
	v_mov_b32_e32 v80, v77
	v_add_f32_e32 v72, 1.0, v76
	v_mul_f32_e32 v85, v82, v83
	v_rcp_f32_e32 v83, v72
	v_mul_f32_e32 v72, v78, v84
	v_exp_f32_e32 v76, v72
	v_mov_b32_e32 v82, v73
	v_pk_mul_f32 v[72:73], v[80:81], v[82:83]
	v_mov_b32_e32 v80, v78
	v_mul_f32_e32 v77, v72, v73
	v_add_f32_e32 v72, 1.0, v76
	v_rcp_f32_e32 v73, v72
	v_mul_f32_e32 v72, v79, v84
	v_exp_f32_e32 v76, v72
	v_mov_b32_e32 v72, v74
	v_pk_mul_f32 v[72:73], v[80:81], v[72:73]
	v_mov_b32_e32 v80, v79
	v_mul_f32_e32 v74, v72, v73
	v_add_f32_e32 v72, 1.0, v76
	v_rcp_f32_e32 v73, v72
	v_mul_f32_e32 v72, v68, v84
	v_exp_f32_e32 v76, v72
	v_mov_b32_e32 v72, v75
	v_pk_mul_f32 v[72:73], v[80:81], v[72:73]
	v_mov_b32_e32 v80, v68
	v_mul_f32_e32 v75, v72, v73
	v_add_f32_e32 v72, 1.0, v76
	v_mul_f32_e32 v68, v69, v84
	v_rcp_f32_e32 v73, v72
	v_exp_f32_e32 v68, v68
	v_mov_b32_e32 v72, v64
	v_pk_mul_f32 v[72:73], v[80:81], v[72:73]
	v_add_f32_e32 v64, 1.0, v68
	v_mul_f32_e32 v76, v72, v73
	v_rcp_f32_e32 v73, v64
	v_mul_f32_e32 v64, v70, v84
	v_exp_f32_e32 v68, v64
	v_mov_b32_e32 v80, v69
	v_mov_b32_e32 v72, v65
	v_pk_mul_f32 v[64:65], v[80:81], v[72:73]
	v_mov_b32_e32 v80, v70
	v_mul_f32_e32 v72, v64, v65
	v_add_f32_e32 v64, 1.0, v68
	v_rcp_f32_e32 v65, v64
	v_mul_f32_e32 v64, v71, v84
	v_exp_f32_e32 v68, v64
	v_mov_b32_e32 v64, v66
	v_pk_mul_f32 v[64:65], v[80:81], v[64:65]
	v_mov_b32_e32 v80, v71
	v_add_f32_e32 v66, 1.0, v68
	v_rcp_f32_e32 v69, v66
	v_mov_b32_e32 v68, v67
	v_mul_f32_e32 v70, v64, v65
	v_pk_mul_f32 v[64:65], v[80:81], v[68:69]
	v_add_u32_e32 v68, s60, v153
	v_mad_i64_i32 v[68:69], s[30:31], v68, s64, v[112:113]
	v_lshl_add_u64 v[68:69], v[68:69], 0, s[2:3]
	v_lshl_add_u64 v[68:69], v[68:69], 0, s[8:9]
	v_mul_f32_e32 v67, v64, v65
	v_lshl_add_u64 v[68:69], v[68:69], 0, v[136:137]
	v_cvt_pk_bf16_f32 v64, v85, v77
	v_cvt_pk_bf16_f32 v65, v74, v75
	v_cvt_pk_bf16_f32 v66, v76, v72
	v_cvt_pk_bf16_f32 v67, v70, v67
	flat_store_dwordx4 v[68:69], v[64:67]
	ds_read_b32 v64, v157
	s_waitcnt lgkmcnt(0)
; __device__ __forceinline__ u32x4 pack8(f32x4 v0, f32x4 v1) { u32x4 w; w.x = cvt_pk_bf16(v0[0], v0[1]); w.y = cvt_pk_bf16(v0[2], v0[3]); w.z = cvt_pk_bf16(v1[0], v1[1]); w.w = cvt_pk_bf16(v1[2], v1[3]); return w; }
;     __device__ __forceinline__ void operator()(Acc& acc, const Unit& u, int wr, int wc, int fr, int fq, PG8_LAS unsigned char* xl) const {
;     ...
;             for (int m = 0; m < 4; ++m) { const int rl = ai * HALF + wr * 64 + m * 16 + fr; const int row = u.r0 + rl; const float s = S[rl], cs = -LOG2E * s, s2 = s * s;
;                 f32x4 o[2];
; #pragma unroll
;                 for (int n = 0; n < 2; ++n) { const f32x4 g = acc[ai][0][m][n], gu = acc[ai][0][m][n] * acc[ai][1][m][n]; f32x4 r;
; #pragma unroll
;                     for (int e = 0; e < 4; ++e) r[e] = gu[e] * (s2 * __builtin_amdgcn_rcpf(1.f + __builtin_amdgcn_exp2f(cs * g[e])));
;                     o[n] = r; }
;                 *(u32x4*)(H + (size_t)row * ldc + (u.c0 >> 1) + wc * 32 + 8 * fq) = pack8(o[0], o[1]); }
	v_mul_f32_e32 v68, 0xbfb8aa3b, v64
	v_mul_f32_e32 v65, v60, v68
	v_exp_f32_e32 v66, v65
	v_mul_f32_e32 v65, v64, v64
	v_add_f32_e32 v64, 1.0, v66
	v_rcp_f32_e32 v67, v64
	v_mov_b32_e32 v64, v60
	v_mul_f32_e32 v60, v61, v68
	v_exp_f32_e32 v60, v60
	v_mov_b32_e32 v66, v56
	v_pk_mul_f32 v[66:67], v[64:65], v[66:67]
	v_mov_b32_e32 v64, v61
	v_add_f32_e32 v56, 1.0, v60
	v_mul_f32_e32 v69, v66, v67
	v_rcp_f32_e32 v67, v56
	v_mul_f32_e32 v56, v62, v68
	v_exp_f32_e32 v60, v56
	v_mov_b32_e32 v66, v57
	v_pk_mul_f32 v[56:57], v[64:65], v[66:67]
	v_mov_b32_e32 v64, v62
	v_mul_f32_e32 v61, v56, v57
	v_add_f32_e32 v56, 1.0, v60
	v_rcp_f32_e32 v57, v56
	v_mul_f32_e32 v56, v63, v68
	v_exp_f32_e32 v60, v56
	v_mov_b32_e32 v56, v58
	v_pk_mul_f32 v[56:57], v[64:65], v[56:57]
	v_mov_b32_e32 v64, v63
	v_mul_f32_e32 v58, v56, v57
	v_add_f32_e32 v56, 1.0, v60
	v_rcp_f32_e32 v57, v56
	v_mul_f32_e32 v56, v52, v68
	v_exp_f32_e32 v60, v56
	v_mov_b32_e32 v56, v59
	v_pk_mul_f32 v[56:57], v[64:65], v[56:57]
	v_mov_b32_e32 v64, v52
	v_mul_f32_e32 v59, v56, v57
	v_add_f32_e32 v56, 1.0, v60
	v_mul_f32_e32 v52, v53, v68
	v_rcp_f32_e32 v57, v56
	v_exp_f32_e32 v52, v52
	v_mov_b32_e32 v56, v48
	v_pk_mul_f32 v[56:57], v[64:65], v[56:57]
	v_add_f32_e32 v48, 1.0, v52
	v_mul_f32_e32 v60, v56, v57
	v_rcp_f32_e32 v57, v48
	v_mul_f32_e32 v48, v54, v68
	v_exp_f32_e32 v52, v48
	v_mov_b32_e32 v64, v53
	v_mov_b32_e32 v56, v49
	v_pk_mul_f32 v[48:49], v[64:65], v[56:57]
	v_mov_b32_e32 v64, v54
	v_mul_f32_e32 v56, v48, v49
	v_add_f32_e32 v48, 1.0, v52
	v_rcp_f32_e32 v49, v48
	v_mul_f32_e32 v48, v55, v68
	v_exp_f32_e32 v52, v48
	v_mov_b32_e32 v48, v50
	v_pk_mul_f32 v[48:49], v[64:65], v[48:49]
	v_mov_b32_e32 v64, v55
	v_add_f32_e32 v50, 1.0, v52
	v_rcp_f32_e32 v53, v50
	v_mov_b32_e32 v52, v51
	v_mul_f32_e32 v54, v48, v49
	v_pk_mul_f32 v[48:49], v[64:65], v[52:53]
	v_add_u32_e32 v52, s60, v156
	v_mad_i64_i32 v[52:53], s[30:31], v52, s64, v[112:113]
	v_lshl_add_u64 v[52:53], v[52:53], 0, s[2:3]
	v_lshl_add_u64 v[52:53], v[52:53], 0, s[8:9]
	v_mul_f32_e32 v51, v48, v49
	v_lshl_add_u64 v[52:53], v[52:53], 0, v[136:137]
	v_cvt_pk_bf16_f32 v48, v69, v61
	v_cvt_pk_bf16_f32 v49, v58, v59
	v_cvt_pk_bf16_f32 v50, v60, v56
	v_cvt_pk_bf16_f32 v51, v54, v51
	flat_store_dwordx4 v[52:53], v[48:51]
	ds_read_b32 v48, v159
	s_waitcnt lgkmcnt(0)
	v_mul_f32_e32 v52, 0xbfb8aa3b, v48
	v_mul_f32_e32 v49, v44, v52
	v_exp_f32_e32 v50, v49
	v_mul_f32_e32 v49, v48, v48
	v_add_f32_e32 v48, 1.0, v50
	v_rcp_f32_e32 v51, v48
	v_mov_b32_e32 v48, v44
	v_mul_f32_e32 v44, v45, v52
	v_exp_f32_e32 v44, v44
	v_mov_b32_e32 v50, v40
	v_pk_mul_f32 v[50:51], v[48:49], v[50:51]
	v_mov_b32_e32 v48, v45
	v_add_f32_e32 v40, 1.0, v44
	v_mul_f32_e32 v53, v50, v51
	v_rcp_f32_e32 v51, v40
	v_mul_f32_e32 v40, v46, v52
	v_exp_f32_e32 v44, v40
	v_mov_b32_e32 v50, v41
	v_pk_mul_f32 v[40:41], v[48:49], v[50:51]
	v_mov_b32_e32 v48, v46
	v_mul_f32_e32 v45, v40, v41
	v_add_f32_e32 v40, 1.0, v44
	v_rcp_f32_e32 v41, v40
	v_mul_f32_e32 v40, v47, v52
	v_exp_f32_e32 v44, v40
	v_mov_b32_e32 v40, v42
	v_pk_mul_f32 v[40:41], v[48:49], v[40:41]
	v_mov_b32_e32 v48, v47
	v_mul_f32_e32 v42, v40, v41
	v_add_f32_e32 v40, 1.0, v44
	v_rcp_f32_e32 v41, v40
	v_mul_f32_e32 v40, v36, v52
	v_exp_f32_e32 v44, v40
	v_mov_b32_e32 v40, v43
	v_pk_mul_f32 v[40:41], v[48:49], v[40:41]
	v_mov_b32_e32 v48, v36
	v_mul_f32_e32 v43, v40, v41
	v_add_f32_e32 v40, 1.0, v44
	v_mul_f32_e32 v36, v37, v52
	v_rcp_f32_e32 v41, v40
	v_exp_f32_e32 v36, v36
	v_mov_b32_e32 v40, v32
	v_pk_mul_f32 v[40:41], v[48:49], v[40:41]
	v_add_f32_e32 v32, 1.0, v36
	v_mul_f32_e32 v44, v40, v41
	v_rcp_f32_e32 v41, v32
	v_mul_f32_e32 v32, v38, v52
	v_exp_f32_e32 v36, v32
	v_mov_b32_e32 v48, v37
	v_mov_b32_e32 v40, v33
	v_pk_mul_f32 v[32:33], v[48:49], v[40:41]
	v_mov_b32_e32 v48, v38
	v_mul_f32_e32 v40, v32, v33
	v_add_f32_e32 v32, 1.0, v36
	v_rcp_f32_e32 v33, v32
	v_mul_f32_e32 v32, v39, v52
	v_exp_f32_e32 v36, v32
	v_mov_b32_e32 v32, v34
	v_pk_mul_f32 v[32:33], v[48:49], v[32:33]
	v_mov_b32_e32 v48, v39
	v_add_f32_e32 v34, 1.0, v36
	v_rcp_f32_e32 v37, v34
	v_mov_b32_e32 v36, v35
	v_mul_f32_e32 v38, v32, v33
	v_pk_mul_f32 v[32:33], v[48:49], v[36:37]
	v_add_u32_e32 v36, s60, v158
	v_mad_i64_i32 v[36:37], s[30:31], v36, s64, v[112:113]
	v_lshl_add_u64 v[36:37], v[36:37], 0, s[2:3]
	v_lshl_add_u64 v[36:37], v[36:37], 0, s[8:9]
	v_mul_f32_e32 v35, v32, v33
	v_lshl_add_u64 v[36:37], v[36:37], 0, v[136:137]
	v_cvt_pk_bf16_f32 v32, v53, v45
	v_cvt_pk_bf16_f32 v33, v42, v43
	v_cvt_pk_bf16_f32 v34, v44, v40
	v_cvt_pk_bf16_f32 v35, v38, v35
	flat_store_dwordx4 v[36:37], v[32:35]
	ds_read_b32 v32, v161
	s_waitcnt lgkmcnt(0)
; __device__ __forceinline__ u32x4 pack8(f32x4 v0, f32x4 v1) { u32x4 w; w.x = cvt_pk_bf16(v0[0], v0[1]); w.y = cvt_pk_bf16(v0[2], v0[3]); w.z = cvt_pk_bf16(v1[0], v1[1]); w.w = cvt_pk_bf16(v1[2], v1[3]); return w; }
; #define PG8_BAR __builtin_amdgcn_s_barrier()
;     __device__ __forceinline__ void operator()(Acc& acc, const Unit& u, int wr, int wc, int fr, int fq, PG8_LAS unsigned char* xl) const {
;     ...
;             for (int m = 0; m < 4; ++m) { const int rl = ai * HALF + wr * 64 + m * 16 + fr; const int row = u.r0 + rl; const float s = S[rl], cs = -LOG2E * s, s2 = s * s;
;                 f32x4 o[2];
; #pragma unroll
;                 for (int n = 0; n < 2; ++n) { const f32x4 g = acc[ai][0][m][n], gu = acc[ai][0][m][n] * acc[ai][1][m][n]; f32x4 r;
; #pragma unroll
;                     for (int e = 0; e < 4; ++e) r[e] = gu[e] * (s2 * __builtin_amdgcn_rcpf(1.f + __builtin_amdgcn_exp2f(cs * g[e])));
;                     o[n] = r; }
;                 *(u32x4*)(H + (size_t)row * ldc + (u.c0 >> 1) + wc * 32 + 8 * fq) = pack8(o[0], o[1]); }
; template <class Epi, class Sched>
; __device__ __forceinline__ void gemm_phase(PG8_LAS unsigned char* lds, PG8_LAS unsigned char* xl, const Gemm g, const Sched& S, const Epi& E) {
;     ...
;         if (!has_next) break;
; #pragma unroll
;         for (int a = 0; a < 2; ++a)
; #pragma unroll
;             for (int b = 0; b < 2; ++b)
; #pragma unroll
;                 for (int m = 0; m < 4; ++m)
; #pragma unroll
;                     for (int n = 0; n < 2; ++n) acc[a][b][m][n] = (f32x4){0.f, 0.f, 0.f, 0.f};
;         cur = nxt; cA = nA; cB = nB; ++ui;
;         if (wr == 1) PG8_BAR;
	v_mul_f32_e32 v36, 0xbfb8aa3b, v32
	v_mul_f32_e32 v33, v28, v36
	v_exp_f32_e32 v34, v33
	v_mul_f32_e32 v33, v32, v32
	v_add_f32_e32 v32, 1.0, v34
	v_rcp_f32_e32 v35, v32
	v_mov_b32_e32 v32, v28
	v_mul_f32_e32 v28, v29, v36
	v_exp_f32_e32 v28, v28
	v_mov_b32_e32 v34, v24
	v_pk_mul_f32 v[34:35], v[32:33], v[34:35]
	v_mov_b32_e32 v32, v29
	v_add_f32_e32 v24, 1.0, v28
	v_mul_f32_e32 v37, v34, v35
	v_rcp_f32_e32 v35, v24
	v_mul_f32_e32 v24, v30, v36
	v_exp_f32_e32 v28, v24
	v_mov_b32_e32 v34, v25
	v_pk_mul_f32 v[24:25], v[32:33], v[34:35]
	v_mov_b32_e32 v32, v30
	v_mul_f32_e32 v29, v24, v25
	v_add_f32_e32 v24, 1.0, v28
	v_rcp_f32_e32 v25, v24
	v_mul_f32_e32 v24, v31, v36
	v_exp_f32_e32 v28, v24
	v_mov_b32_e32 v24, v26
	v_pk_mul_f32 v[24:25], v[32:33], v[24:25]
	v_mov_b32_e32 v32, v31
	v_mul_f32_e32 v26, v24, v25
	v_add_f32_e32 v24, 1.0, v28
	v_rcp_f32_e32 v25, v24
	v_mul_f32_e32 v24, v20, v36
	v_exp_f32_e32 v28, v24
	v_mov_b32_e32 v24, v27
	v_pk_mul_f32 v[24:25], v[32:33], v[24:25]
	v_mov_b32_e32 v32, v20
	v_mul_f32_e32 v27, v24, v25
	v_add_f32_e32 v24, 1.0, v28
	v_mul_f32_e32 v20, v21, v36
	v_rcp_f32_e32 v25, v24
	v_exp_f32_e32 v20, v20
	v_mov_b32_e32 v24, v16
	v_pk_mul_f32 v[24:25], v[32:33], v[24:25]
	v_add_f32_e32 v16, 1.0, v20
	v_mul_f32_e32 v28, v24, v25
	v_rcp_f32_e32 v25, v16
	v_mul_f32_e32 v16, v22, v36
	v_exp_f32_e32 v20, v16
	v_mov_b32_e32 v32, v21
	v_mov_b32_e32 v24, v17
	v_pk_mul_f32 v[16:17], v[32:33], v[24:25]
	v_mov_b32_e32 v32, v22
	v_mul_f32_e32 v24, v16, v17
	v_add_f32_e32 v16, 1.0, v20
	v_rcp_f32_e32 v17, v16
	v_mul_f32_e32 v16, v23, v36
	v_exp_f32_e32 v20, v16
	v_mov_b32_e32 v16, v18
	v_pk_mul_f32 v[16:17], v[32:33], v[16:17]
	v_mov_b32_e32 v32, v23
	v_add_f32_e32 v18, 1.0, v20
	v_rcp_f32_e32 v21, v18
	v_mov_b32_e32 v20, v19
	v_mul_f32_e32 v22, v16, v17
	v_pk_mul_f32 v[16:17], v[32:33], v[20:21]
	v_add_u32_e32 v20, s60, v160
	v_mad_i64_i32 v[20:21], s[30:31], v20, s64, v[112:113]
	v_lshl_add_u64 v[20:21], v[20:21], 0, s[2:3]
	v_lshl_add_u64 v[20:21], v[20:21], 0, s[8:9]
	v_mul_f32_e32 v19, v16, v17
	v_lshl_add_u64 v[20:21], v[20:21], 0, v[136:137]
	v_cvt_pk_bf16_f32 v16, v37, v29
	v_cvt_pk_bf16_f32 v17, v26, v27
	v_cvt_pk_bf16_f32 v18, v28, v24
	v_cvt_pk_bf16_f32 v19, v22, v19
	flat_store_dwordx4 v[20:21], v[16:19]
	ds_read_b32 v16, v163
	s_waitcnt lgkmcnt(0)
	v_mul_f32_e32 v20, 0xbfb8aa3b, v16
	v_mul_f32_e32 v17, v12, v20
	v_exp_f32_e32 v18, v17
	v_mul_f32_e32 v17, v16, v16
	v_add_f32_e32 v16, 1.0, v18
	v_rcp_f32_e32 v19, v16
	v_mov_b32_e32 v16, v12
	v_mul_f32_e32 v12, v13, v20
	v_exp_f32_e32 v12, v12
	v_mov_b32_e32 v18, v8
	v_pk_mul_f32 v[18:19], v[16:17], v[18:19]
	v_mov_b32_e32 v16, v13
	v_add_f32_e32 v8, 1.0, v12
	v_mul_f32_e32 v21, v18, v19
	v_rcp_f32_e32 v19, v8
	v_mul_f32_e32 v8, v14, v20
	v_exp_f32_e32 v12, v8
	v_mov_b32_e32 v18, v9
	v_pk_mul_f32 v[8:9], v[16:17], v[18:19]
	v_mov_b32_e32 v16, v14
	v_mul_f32_e32 v13, v8, v9
	v_add_f32_e32 v8, 1.0, v12
	v_rcp_f32_e32 v9, v8
	v_mul_f32_e32 v8, v15, v20
	v_exp_f32_e32 v12, v8
	v_mov_b32_e32 v8, v10
	v_pk_mul_f32 v[8:9], v[16:17], v[8:9]
	v_mov_b32_e32 v16, v15
	v_mul_f32_e32 v10, v8, v9
	v_add_f32_e32 v8, 1.0, v12
	v_rcp_f32_e32 v9, v8
	v_mul_f32_e32 v8, v4, v20
	v_exp_f32_e32 v12, v8
	v_mov_b32_e32 v8, v11
	v_pk_mul_f32 v[8:9], v[16:17], v[8:9]
	v_mov_b32_e32 v16, v4
	v_mul_f32_e32 v11, v8, v9
	v_add_f32_e32 v8, 1.0, v12
	v_mul_f32_e32 v4, v5, v20
	v_rcp_f32_e32 v9, v8
	v_exp_f32_e32 v4, v4
	v_mov_b32_e32 v8, v0
	v_pk_mul_f32 v[8:9], v[16:17], v[8:9]
	v_add_f32_e32 v0, 1.0, v4
	v_mul_f32_e32 v12, v8, v9
	v_rcp_f32_e32 v9, v0
	v_mul_f32_e32 v0, v6, v20
	v_exp_f32_e32 v4, v0
	v_mov_b32_e32 v16, v5
	v_mov_b32_e32 v8, v1
	v_pk_mul_f32 v[0:1], v[16:17], v[8:9]
	v_mov_b32_e32 v16, v6
	v_mul_f32_e32 v8, v0, v1
	v_add_f32_e32 v0, 1.0, v4
	v_rcp_f32_e32 v1, v0
	v_mul_f32_e32 v0, v7, v20
	v_exp_f32_e32 v4, v0
	v_mov_b32_e32 v0, v2
	v_pk_mul_f32 v[0:1], v[16:17], v[0:1]
	v_mov_b32_e32 v16, v7
	v_add_f32_e32 v2, 1.0, v4
	v_rcp_f32_e32 v5, v2
	v_mov_b32_e32 v4, v3
	v_mul_f32_e32 v6, v0, v1
	v_pk_mul_f32 v[0:1], v[16:17], v[4:5]
	v_add_u32_e32 v4, s60, v162
	v_mad_i64_i32 v[4:5], s[30:31], v4, s64, v[112:113]
	v_lshl_add_u64 v[4:5], v[4:5], 0, s[2:3]
	v_lshl_add_u64 v[4:5], v[4:5], 0, s[8:9]
	v_mul_f32_e32 v3, v0, v1
	v_lshl_add_u64 v[4:5], v[4:5], 0, v[136:137]
	s_mov_b64 s[2:3], -1
	v_cvt_pk_bf16_f32 v0, v21, v13
	v_cvt_pk_bf16_f32 v1, v10, v11
	v_cvt_pk_bf16_f32 v2, v12, v8
	v_cvt_pk_bf16_f32 v3, v6, v3
	flat_store_dwordx4 v[4:5], v[0:3]
	s_cbranch_vccnz .LBB0_821
	s_andn2_b64 vcc, exec, s[10:11]
	s_cbranch_vccnz .LBB0_820
	s_barrier
	s_branch .LBB0_820

; #define PH(n) if (ONLY < 0 || ONLY == (n))
; #define WSB(off) ((bf16*)((unsigned char*)KARG(20) + (off)))
; #define WSF(off) ((float*)((unsigned char*)KARG(20) + (off)))
; __global__ void __launch_bounds__(NWAVES * 64, 2) mk_fwd(Args args) {
;     ...
;     PH(8) { PHASE_VARS
;         pg8::Gemm g{WSB(WS_XN), WSB(WS_WGU), DM, DM, DM}; pg8::Sched2D S; S.init(T, 2 * DFF, G, bx, DM, DM);
;         pg8::EpiSwiGLU E{WSB(WS_HMID), DFF, WSF(WS_SS2)};
;         pg8::gemm_phase(lds, xl, g, S, E);
;     } }
	.amdhsa_kernel _Z6mk_fwd4Args
		.amdhsa_group_segment_fixed_size 0
		.amdhsa_private_segment_fixed_size 0
		.amdhsa_kernarg_size 424
		.amdhsa_user_sgpr_count 2
		.amdhsa_user_sgpr_dispatch_ptr 0
		.amdhsa_user_sgpr_queue_ptr 0
		.amdhsa_user_sgpr_kernarg_segment_ptr 1
		.amdhsa_user_sgpr_dispatch_id 0
		.amdhsa_user_sgpr_kernarg_preload_length 0
		.amdhsa_user_sgpr_kernarg_preload_offset 0
		.amdhsa_user_sgpr_private_segment_size 0
		.amdhsa_uses_dynamic_stack 0
		.amdhsa_enable_private_segment 0
		.amdhsa_system_sgpr_workgroup_id_x 1
		.amdhsa_system_sgpr_workgroup_id_y 0
		.amdhsa_system_sgpr_workgroup_id_z 0
		.amdhsa_system_sgpr_workgroup_info 0
		.amdhsa_system_vgpr_workitem_id 2
		.amdhsa_next_free_vgpr 256
		.amdhsa_next_free_sgpr 102
		.amdhsa_accum_offset 256
		.amdhsa_reserve_vcc 1
		.amdhsa_float_round_mode_32 0
		.amdhsa_float_round_mode_16_64 0
		.amdhsa_float_denorm_mode_32 3
		.amdhsa_float_denorm_mode_16_64 3
		.amdhsa_dx10_clamp 1
		.amdhsa_ieee_mode 1
		.amdhsa_fp16_overflow 0
		.amdhsa_tg_split 0
		.amdhsa_exception_fp_ieee_invalid_op 0
		.amdhsa_exception_fp_denorm_src 0
		.amdhsa_exception_fp_ieee_div_zero 0
		.amdhsa_exception_fp_ieee_overflow 0
		.amdhsa_exception_fp_ieee_underflow 0
		.amdhsa_exception_fp_ieee_inexact 0
		.amdhsa_exception_int_div_zero 0
	.end_amdhsa_kernel

; #define PH(n) if (ONLY < 0 || ONLY == (n))
; #define WSB(off) ((bf16*)((unsigned char*)KARG(20) + (off)))
; #define WSF(off) ((float*)((unsigned char*)KARG(20) + (off)))
; __global__ void __launch_bounds__(NWAVES * 64, 2) mk_fwd(Args args) {
;     ...
;     PH(8) { PHASE_VARS
;         pg8::Gemm g{WSB(WS_XN), WSB(WS_WGU), DM, DM, DM}; pg8::Sched2D S; S.init(T, 2 * DFF, G, bx, DM, DM);
;         pg8::EpiSwiGLU E{WSB(WS_HMID), DFF, WSF(WS_SS2)};
;         pg8::gemm_phase(lds, xl, g, S, E);
;     } }
amdhsa.kernels:
  - .agpr_count:     0
    .args:
      - .offset:         0
        .size:           168
        .value_kind:     by_value
      - .offset:         168
        .size:           4
        .value_kind:     hidden_block_count_x
      - .offset:         172
        .size:           4
        .value_kind:     hidden_block_count_y
      - .offset:         176
        .size:           4
        .value_kind:     hidden_block_count_z
      - .offset:         180
        .size:           2
        .value_kind:     hidden_group_size_x
      - .offset:         182
        .size:           2
        .value_kind:     hidden_group_size_y
      - .offset:         184
        .size:           2
        .value_kind:     hidden_group_size_z
      - .offset:         186
        .size:           2
        .value_kind:     hidden_remainder_x
      - .offset:         188
        .size:           2
        .value_kind:     hidden_remainder_y
      - .offset:         190
        .size:           2
        .value_kind:     hidden_remainder_z
      - .offset:         208
        .size:           8
        .value_kind:     hidden_global_offset_x
      - .offset:         216
        .size:           8
        .value_kind:     hidden_global_offset_y
      - .offset:         224
        .size:           8
        .value_kind:     hidden_global_offset_z
      - .offset:         232
        .size:           2
        .value_kind:     hidden_grid_dims
      - .offset:         256
        .size:           8
        .value_kind:     hidden_multigrid_sync_arg
      - .offset:         288
        .size:           4
        .value_kind:     hidden_dynamic_lds_size
    .group_segment_fixed_size: 0
    .kernarg_segment_align: 8
    .kernarg_segment_size: 424
    .language:       OpenCL C
    .language_version:
      - 2
      - 0
    .max_flat_workgroup_size: 512
    .name:           _Z6mk_fwd4Args
    .private_segment_fixed_size: 0
    .sgpr_count:     108
    .sgpr_spill_count: 6
    .symbol:         _Z6mk_fwd4Args.kd
    .uniform_work_group_size: 1
    .uses_dynamic_stack: false
    .vgpr_count:     256
    .vgpr_spill_count: 0
    .wavefront_size: 64
